# pvprio_s + up K-loop: vmcnt(6) instead of vmcnt(8) at the end of the two heavy (6-DMA) load phases (tighter pacing)
# speedup vs baseline: 1.0075x; 1.0075x over previous
; #define PG8_STAGE(bufoff, gbase, voff) glds16s2((voff)[0], (voff)[1], (const void*)(gbase), ldsn + (unsigned)(bufoff))
; #define PG8_LDA(dst, b, h) do { _Pragma("unroll") for (int m = 0; m < 4; ++m) _Pragma("unroll") for (int k = 0; k < 2; ++k) dst[m][k] = *(const LAS bf16x8*)(lds + PG8_SA(b, h) + aoff + m * 2048 + k * 1024); } while (0)
; #define PG8_LDB(dst, b, h) do { _Pragma("unroll") for (int n = 0; n < 2; ++n) _Pragma("unroll") for (int k = 0; k < 2; ++k) dst[n][k] = *(const LAS bf16x8*)(lds + PG8_SB(b, h) + boff + n * 2048 + k * 1024); } while (0)
; #define PG8_MMA(ai, bj, At, Bt) do { __builtin_amdgcn_s_setprio(1); _Pragma("unroll") for (int m = 0; m < 4; ++m) _Pragma("unroll") for (int n = 0; n < 2; ++n) _Pragma("unroll") for (int k = 0; k < 2; ++k) \
;         acc[ai][bj][m][n] = __builtin_amdgcn_mfma_f32_16x16x32_bf16(Bt[n][k], At[m][k], acc[ai][bj][m][n], 0, 0, 0); __builtin_amdgcn_s_setprio(0); } while (0)
; #define PG8_WAIT_V(n) asm volatile("s_waitcnt vmcnt(" #n ")" ::: "memory")
; #define PG8_WAIT_L(n) asm volatile("s_waitcnt lgkmcnt(" #n ")" ::: "memory")
; #define PG8_BAR __builtin_amdgcn_s_barrier()
; #define PG8_SCHED __builtin_amdgcn_sched_barrier(0)
; template <class Epi, bool ALIGN_EPI, bool EARLY_DRAIN = true, class Pre = NoPre>
; __device__ __forceinline__ void gemm_phase(LAS unsigned char* lds, const Gemm g, const StaticOrder& S, const Epi& E, int wv, const Pre& pre = Pre()) {
;     ...
;             PG8_WAIT_L(0); PG8_BAR; PG8_MMA(0, 0, At, B0); PG8_MMA(0, 1, At, B1); PG8_BAR; PG8_SCHED;
;             PG8_LDA(At, 0, 1); PG8_STAGE(PG8_SB(0, 0), b2, voffB); PG8_STAGE(PG8_SB(0, 1), b2 + bhs, voffB); PG8_STAGE(PG8_SA(0, 0), a2, voffA);
;             if (!lf_) PG8_WAIT_V(8);
;             PG8_WAIT_L(0); PG8_BAR; PG8_MMA(1, 0, At, B0); PG8_MMA(1, 1, At, B1); PG8_BAR; PG8_SCHED;
;             PG8_LDB(B0, 1, 0); PG8_LDB(B1, 1, 1); PG8_SCHED; PG8_LDA(At, 1, 0); PG8_STAGE(PG8_SA(0, 1), a2 + ahs, voffA);
;             if (!lf_) PG8_WAIT_V(8);
;             PG8_WAIT_L(0); PG8_BAR; PG8_MMA(0, 0, At, B0); PG8_MMA(0, 1, At, B1); PG8_BAR; PG8_SCHED;
;             PG8_LDA(At, 1, 1); PG8_STAGE(PG8_SB(1, 0), b3, voffB); PG8_STAGE(PG8_SB(1, 1), b3 + bhs, voffB); PG8_STAGE(PG8_SA(1, 0), a3, voffA);
;             PG8_WAIT_V(8); PG8_WAIT_L(0); PG8_BAR; PG8_MMA(1, 0, At, B0); PG8_MMA(1, 1, At, B1); PG8_BAR; PG8_SCHED;
.LBB0_558:
	s_add_u32 s14, s86, 0x80
	s_waitcnt lgkmcnt(0)
	s_addc_u32 s15, s87, 0
	s_add_u32 s40, s84, 0x80
	s_addc_u32 s41, s85, 0
	s_barrier
	s_setprio 1
	v_mfma_f32_16x16x32_bf16 v[78:81], v[178:181], v[154:157], v[78:81]
	v_mfma_f32_16x16x32_bf16 v[146:149], v[182:185], v[202:205], v[78:81]
	v_mfma_f32_16x16x32_bf16 v[78:81], v[178:181], v[126:129], v[92:95]
	v_mfma_f32_16x16x32_bf16 v[70:73], v[162:165], v[154:157], v[70:73]
	v_mfma_f32_16x16x32_bf16 v[74:77], v[162:165], v[126:129], v[74:77]
	v_mfma_f32_16x16x32_bf16 v[150:153], v[182:185], v[158:161], v[78:81]
	v_mfma_f32_16x16x32_bf16 v[78:81], v[162:165], v[194:197], v[82:85]
	v_mfma_f32_16x16x32_bf16 v[66:69], v[178:181], v[194:197], v[66:69]
	v_mfma_f32_16x16x32_bf16 v[54:57], v[162:165], v[186:189], v[54:57]
	v_mfma_f32_16x16x32_bf16 v[50:53], v[178:181], v[186:189], v[50:53]
	v_mfma_f32_16x16x32_bf16 v[70:73], v[174:177], v[202:205], v[70:73]
	v_mfma_f32_16x16x32_bf16 v[74:77], v[174:177], v[158:161], v[74:77]
	v_mfma_f32_16x16x32_bf16 v[82:85], v[174:177], v[198:201], v[78:81]
	v_mfma_f32_16x16x32_bf16 v[66:69], v[182:185], v[198:201], v[66:69]
	v_mfma_f32_16x16x32_bf16 v[54:57], v[174:177], v[190:193], v[54:57]
	v_mfma_f32_16x16x32_bf16 v[50:53], v[182:185], v[190:193], v[50:53]
	s_setprio 0
	s_setprio 1
	v_mfma_f32_16x16x32_bf16 v[78:81], v[138:141], v[154:157], v[86:89]
	v_mfma_f32_16x16x32_bf16 v[88:91], v[142:145], v[202:205], v[78:81]
	v_mfma_f32_16x16x32_bf16 v[78:81], v[166:169], v[154:157], v[102:105]
	v_mfma_f32_16x16x32_bf16 v[154:157], v[170:173], v[202:205], v[78:81]
	v_mfma_f32_16x16x32_bf16 v[78:81], v[138:141], v[126:129], v[96:99]
	v_mfma_f32_16x16x32_bf16 v[98:101], v[142:145], v[158:161], v[78:81]
	v_mfma_f32_16x16x32_bf16 v[78:81], v[166:169], v[126:129], v[118:121]
	v_mfma_f32_16x16x32_bf16 v[158:161], v[170:173], v[158:161], v[78:81]
	v_mfma_f32_16x16x32_bf16 v[78:81], v[138:141], v[194:197], v[122:125]
	v_mfma_f32_16x16x32_bf16 v[126:129], v[142:145], v[198:201], v[78:81]
	v_mfma_f32_16x16x32_bf16 v[78:81], v[166:169], v[194:197], v[110:113]
	v_mfma_f32_16x16x32_bf16 v[62:65], v[138:141], v[186:189], v[62:65]
	v_mfma_f32_16x16x32_bf16 v[58:61], v[166:169], v[186:189], v[58:61]
	v_mfma_f32_16x16x32_bf16 v[110:113], v[170:173], v[198:201], v[78:81]
	v_mfma_f32_16x16x32_bf16 v[62:65], v[142:145], v[190:193], v[62:65]
	v_mfma_f32_16x16x32_bf16 v[58:61], v[170:173], v[190:193], v[58:61]
	s_setprio 0
	s_barrier
	s_nop 0
	ds_read_b128 v[78:81], v245 offset:49152
	ds_read_b128 v[92:95], v245 offset:50176
	ds_read_b128 v[102:105], v245 offset:51200
	ds_read_b128 v[118:121], v245 offset:52224
	ds_read_b128 v[122:125], v245 offset:53248
	ds_read_b128 v[186:189], v245 offset:54272
	ds_read_b128 v[190:193], v245 offset:55296
	ds_read_b128 v[194:197], v245 offset:56320
	s_mov_b32 m0, s64
	s_nop 0
	global_load_lds_dwordx4 v251, s[40:41]
	s_add_u32 m0, m0, 0x2000
	s_nop 0
	global_load_lds_dwordx4 v247, s[40:41]
	s_add_u32 s40, s84, 0x580080
	s_addc_u32 s41, s85, 0
	s_mov_b32 m0, s66
	s_nop 0
	global_load_lds_dwordx4 v251, s[40:41]
	s_add_u32 m0, m0, 0x2000
	s_nop 0
	global_load_lds_dwordx4 v247, s[40:41]
	s_nop 0
	s_mov_b32 m0, s65
	s_nop 0
	global_load_lds_dwordx4 v250, s[14:15]
	s_add_u32 m0, m0, 0x2000
	s_nop 0
	global_load_lds_dwordx4 v246, s[14:15]
	s_waitcnt vmcnt(6)
	s_waitcnt lgkmcnt(0)
	s_barrier
	s_setprio 1
	v_mfma_f32_16x16x32_bf16 v[38:41], v[162:165], v[78:81], v[38:41]
	v_mfma_f32_16x16x32_bf16 v[34:37], v[178:181], v[78:81], v[34:37]
	v_mfma_f32_16x16x32_bf16 v[26:29], v[162:165], v[102:105], v[26:29]
	v_mfma_f32_16x16x32_bf16 v[18:21], v[178:181], v[102:105], v[18:21]
	v_mfma_f32_16x16x32_bf16 v[6:9], v[162:165], v[122:125], v[6:9]
	v_mfma_f32_16x16x32_bf16 v[2:5], v[178:181], v[122:125], v[2:5]
	v_mfma_f32_16x16x32_bf16 v[106:109], v[162:165], v[190:193], v[106:109]
	v_mfma_f32_16x16x32_bf16 v[130:133], v[178:181], v[190:193], v[130:133]
	v_mfma_f32_16x16x32_bf16 v[38:41], v[174:177], v[92:95], v[38:41]
	v_mfma_f32_16x16x32_bf16 v[34:37], v[182:185], v[92:95], v[34:37]
	v_mfma_f32_16x16x32_bf16 v[26:29], v[174:177], v[118:121], v[26:29]
	v_mfma_f32_16x16x32_bf16 v[18:21], v[182:185], v[118:121], v[18:21]
	v_mfma_f32_16x16x32_bf16 v[6:9], v[174:177], v[186:189], v[6:9]
	v_mfma_f32_16x16x32_bf16 v[2:5], v[182:185], v[186:189], v[2:5]
	v_mfma_f32_16x16x32_bf16 v[106:109], v[174:177], v[194:197], v[106:109]
	v_mfma_f32_16x16x32_bf16 v[162:165], v[182:185], v[194:197], v[130:133]
	s_setprio 0
	s_setprio 1
	v_mfma_f32_16x16x32_bf16 v[46:49], v[138:141], v[78:81], v[46:49]
	v_mfma_f32_16x16x32_bf16 v[42:45], v[166:169], v[78:81], v[42:45]
	v_mfma_f32_16x16x32_bf16 v[78:81], v[138:141], v[190:193], v[114:117]
	v_mfma_f32_16x16x32_bf16 v[30:33], v[138:141], v[102:105], v[30:33]
	v_mfma_f32_16x16x32_bf16 v[22:25], v[166:169], v[102:105], v[22:25]
	v_mfma_f32_16x16x32_bf16 v[14:17], v[138:141], v[122:125], v[14:17]
	v_mfma_f32_16x16x32_bf16 v[10:13], v[166:169], v[122:125], v[10:13]
	v_mfma_f32_16x16x32_bf16 v[114:117], v[142:145], v[194:197], v[78:81]
	v_mfma_f32_16x16x32_bf16 v[78:81], v[166:169], v[190:193], v[134:137]
	v_mfma_f32_16x16x32_bf16 v[46:49], v[142:145], v[92:95], v[46:49]
	v_mfma_f32_16x16x32_bf16 v[42:45], v[170:173], v[92:95], v[42:45]
	v_mfma_f32_16x16x32_bf16 v[30:33], v[142:145], v[118:121], v[30:33]
	v_mfma_f32_16x16x32_bf16 v[22:25], v[170:173], v[118:121], v[22:25]
	v_mfma_f32_16x16x32_bf16 v[14:17], v[142:145], v[186:189], v[14:17]
	v_mfma_f32_16x16x32_bf16 v[10:13], v[170:173], v[186:189], v[10:13]
	v_mfma_f32_16x16x32_bf16 v[166:169], v[170:173], v[194:197], v[78:81]
	s_setprio 0
	s_barrier
	s_add_i32 s0, s0, 2
	s_add_u32 s51, s51, 0x100
	s_addc_u32 s52, s52, 0
	s_add_u32 s53, s53, 0x100
	s_addc_u32 s61, s61, 0
	s_add_u32 s42, s42, 0x100
	s_addc_u32 s43, s43, 0
	s_cmp_gt_u32 s0, 13
	s_cbranch_scc1 .LBB0_565

; #define PG8_STAGE(bufoff, gbase, voff) glds16s2((voff)[0], (voff)[1], (const void*)(gbase), ldsn + (unsigned)(bufoff))
; #define PG8_LDA(dst, b, h) do { _Pragma("unroll") for (int m = 0; m < 4; ++m) _Pragma("unroll") for (int k = 0; k < 2; ++k) dst[m][k] = *(const LAS bf16x8*)(lds + PG8_SA(b, h) + aoff + m * 2048 + k * 1024); } while (0)
; #define PG8_LDB(dst, b, h) do { _Pragma("unroll") for (int n = 0; n < 2; ++n) _Pragma("unroll") for (int k = 0; k < 2; ++k) dst[n][k] = *(const LAS bf16x8*)(lds + PG8_SB(b, h) + boff + n * 2048 + k * 1024); } while (0)
; #define PG8_MMA(ai, bj, At, Bt) do { __builtin_amdgcn_s_setprio(1); _Pragma("unroll") for (int m = 0; m < 4; ++m) _Pragma("unroll") for (int n = 0; n < 2; ++n) _Pragma("unroll") for (int k = 0; k < 2; ++k) \
;         acc[ai][bj][m][n] = __builtin_amdgcn_mfma_f32_16x16x32_bf16(Bt[n][k], At[m][k], acc[ai][bj][m][n], 0, 0, 0); __builtin_amdgcn_s_setprio(0); } while (0)
; #define PG8_WAIT_V(n) asm volatile("s_waitcnt vmcnt(" #n ")" ::: "memory")
; #define PG8_WAIT_L(n) asm volatile("s_waitcnt lgkmcnt(" #n ")" ::: "memory")
; #define PG8_BAR __builtin_amdgcn_s_barrier()
; #define PG8_SCHED __builtin_amdgcn_sched_barrier(0)
; template <class Epi, bool ALIGN_EPI, bool EARLY_DRAIN = true, class Pre = NoPre>
; __device__ __forceinline__ void gemm_phase(LAS unsigned char* lds, const Gemm g, const StaticOrder& S, const Epi& E, int wv, const Pre& pre = Pre()) {
;     ...
;             PG8_WAIT_L(0); PG8_BAR; PG8_MMA(0, 0, At, B0); PG8_MMA(0, 1, At, B1); PG8_BAR; PG8_SCHED;
;             PG8_LDA(At, 0, 1); PG8_STAGE(PG8_SB(0, 0), b2, voffB); PG8_STAGE(PG8_SB(0, 1), b2 + bhs, voffB); PG8_STAGE(PG8_SA(0, 0), a2, voffA);
;             if (!lf_) PG8_WAIT_V(8);
;             PG8_WAIT_L(0); PG8_BAR; PG8_MMA(1, 0, At, B0); PG8_MMA(1, 1, At, B1); PG8_BAR; PG8_SCHED;
;             PG8_LDB(B0, 1, 0); PG8_LDB(B1, 1, 1); PG8_SCHED; PG8_LDA(At, 1, 0); PG8_STAGE(PG8_SA(0, 1), a2 + ahs, voffA);
.LBB0_561:
	s_waitcnt lgkmcnt(0)
	s_cmp_eq_u32 s0, 12
	s_cselect_b32 s87, s71, s52
	s_cselect_b32 s86, s70, s51
	s_cselect_b32 s85, s47, s61
	s_cselect_b32 s84, s50, s53
	s_barrier
	s_setprio 1
	v_mfma_f32_16x16x32_bf16 v[70:73], v[130:133], v[102:105], v[70:73]
	v_mfma_f32_16x16x32_bf16 v[78:81], v[178:181], v[102:105], v[146:149]
	v_mfma_f32_16x16x32_bf16 v[74:77], v[130:133], v[118:121], v[74:77]
	v_mfma_f32_16x16x32_bf16 v[92:95], v[178:181], v[118:121], v[150:153]
	v_mfma_f32_16x16x32_bf16 v[82:85], v[130:133], v[194:197], v[82:85]
	v_mfma_f32_16x16x32_bf16 v[66:69], v[178:181], v[194:197], v[66:69]
	v_mfma_f32_16x16x32_bf16 v[54:57], v[130:133], v[186:189], v[54:57]
	v_mfma_f32_16x16x32_bf16 v[50:53], v[178:181], v[186:189], v[50:53]
	v_mfma_f32_16x16x32_bf16 v[70:73], v[174:177], v[202:205], v[70:73]
	v_mfma_f32_16x16x32_bf16 v[78:81], v[182:185], v[202:205], v[78:81]
	v_mfma_f32_16x16x32_bf16 v[74:77], v[174:177], v[122:125], v[74:77]
	v_mfma_f32_16x16x32_bf16 v[92:95], v[182:185], v[122:125], v[92:95]
	v_mfma_f32_16x16x32_bf16 v[82:85], v[174:177], v[198:201], v[82:85]
	v_mfma_f32_16x16x32_bf16 v[66:69], v[182:185], v[198:201], v[66:69]
	v_mfma_f32_16x16x32_bf16 v[54:57], v[174:177], v[190:193], v[54:57]
	v_mfma_f32_16x16x32_bf16 v[50:53], v[182:185], v[190:193], v[50:53]
	s_setprio 0
	s_setprio 1
	v_mfma_f32_16x16x32_bf16 v[96:99], v[134:137], v[118:121], v[98:101]
	v_mfma_f32_16x16x32_bf16 v[118:121], v[142:145], v[118:121], v[158:161]
	v_mfma_f32_16x16x32_bf16 v[86:89], v[134:137], v[102:105], v[88:91]
	v_mfma_f32_16x16x32_bf16 v[102:105], v[142:145], v[102:105], v[154:157]
	v_mfma_f32_16x16x32_bf16 v[96:99], v[138:141], v[122:125], v[96:99]
	v_mfma_f32_16x16x32_bf16 v[118:121], v[170:173], v[122:125], v[118:121]
	v_mfma_f32_16x16x32_bf16 v[122:125], v[134:137], v[194:197], v[126:129]
	v_mfma_f32_16x16x32_bf16 v[110:113], v[142:145], v[194:197], v[110:113]
	v_mfma_f32_16x16x32_bf16 v[62:65], v[134:137], v[186:189], v[62:65]
	v_mfma_f32_16x16x32_bf16 v[58:61], v[142:145], v[186:189], v[58:61]
	v_mfma_f32_16x16x32_bf16 v[86:89], v[138:141], v[202:205], v[86:89]
	v_mfma_f32_16x16x32_bf16 v[102:105], v[170:173], v[202:205], v[102:105]
	v_mfma_f32_16x16x32_bf16 v[122:125], v[138:141], v[198:201], v[122:125]
	v_mfma_f32_16x16x32_bf16 v[110:113], v[170:173], v[198:201], v[110:113]
	v_mfma_f32_16x16x32_bf16 v[62:65], v[138:141], v[190:193], v[62:65]
	v_mfma_f32_16x16x32_bf16 v[58:61], v[170:173], v[190:193], v[58:61]
	s_setprio 0
	s_barrier
	ds_read_b128 v[190:193], v245 offset:16384
	ds_read_b128 v[194:197], v245 offset:17408
	ds_read_b128 v[158:161], v245 offset:18432
	ds_read_b128 v[186:189], v245 offset:19456
	ds_read_b128 v[150:153], v245 offset:20480
	ds_read_b128 v[154:157], v245 offset:21504
	ds_read_b128 v[126:129], v245 offset:22528
	ds_read_b128 v[146:149], v245 offset:23552
	s_mov_b32 m0, s22
	s_nop 0
	global_load_lds_dwordx4 v251, s[84:85]
	s_add_u32 m0, m0, 0x2000
	s_nop 0
	global_load_lds_dwordx4 v247, s[84:85]
	s_add_u32 s14, s84, 0x580000
	s_addc_u32 s15, s85, 0
	s_mov_b32 m0, s23
	s_nop 0
	global_load_lds_dwordx4 v251, s[14:15]
	s_add_u32 m0, m0, 0x2000
	s_nop 0
	global_load_lds_dwordx4 v247, s[14:15]
	s_mov_b32 m0, s13
	s_nop 0
	global_load_lds_dwordx4 v250, s[86:87]
	s_add_u32 m0, m0, 0x2000
	s_nop 0
	global_load_lds_dwordx4 v246, s[86:87]
	s_waitcnt vmcnt(6)
